# P1 column-tile kinds permuted so each workgroup gets a balanced mix of heavy and light epilogues
# speedup vs baseline: 1.0182x; 1.0006x over previous
.LBB0_113:
	v_readlane_b32 s9, v241, 19
	s_mov_b32 s48, s9
	v_readlane_b32 s9, v241, 20
	s_mov_b32 s46, s9
	s_mov_b32 s100, 0x82465310
	s_mov_b32 s101, 0x7
	s_lshr_b32 s99, s46, 1
	s_lshl_b32 s99, s99, 2
	s_lshr_b64 s[100:101], s[100:101], s99
	s_and_b32 s100, s100, 15
	s_and_b32 s99, s46, 1
	s_lshl_b32 s100, s100, 1
	s_or_b32 s46, s100, s99
	s_load_dwordx2 s[38:39], s[28:29], 0xa8
	s_andn2_b64 vcc, exec, s[40:41]
	s_cbranch_vccz .LBB0_331

.LBB0_125:
	s_andn2_b64 vcc, exec, s[74:75]
	s_mov_b64 s[76:77], 0
	s_cbranch_vccnz .LBB0_127
	s_ashr_i32 s47, s50, 31
	s_lshr_b32 s47, s47, 29
	s_add_i32 s47, s50, s47
	s_ashr_i32 s49, s47, 3
	s_and_b32 s47, s47, -8
	s_sub_i32 s47, s50, s47
	s_cmp_lt_i32 s47, 0
	s_movk_i32 s50, 0x91
	s_cselect_b32 s50, s50, 0x90
	s_mul_i32 s47, s47, s50
	s_add_i32 s47, s47, s49
	s_mul_hi_i32 s49, s47, 0x38e38e39
	s_lshr_b32 s50, s49, 31
	s_ashr_i32 s49, s49, 3
	s_add_i32 s49, s49, s50
	s_lshl_b32 s50, s49, 1
	s_sub_i32 s51, 64, s50
	s_min_i32 s51, s51, 2
	s_abs_i32 s56, s51
	v_cvt_f32_u32_e32 v0, s56
	s_sub_i32 s71, 0, s56
	s_mul_i32 s49, s49, 36
	s_sub_i32 s47, s47, s49
	v_rcp_iflag_f32_e32 v0, v0
	s_abs_i32 s49, s47
	s_xor_b32 s70, s47, s51
	s_ashr_i32 s70, s70, 31
	v_mul_f32_e32 v0, 0x4f7ffffe, v0
	v_cvt_u32_f32_e32 v0, v0
	s_mov_b64 s[76:77], -1
	v_readfirstlane_b32 s72, v0
	s_mul_i32 s71, s71, s72
	s_mul_hi_u32 s71, s72, s71
	s_add_i32 s72, s72, s71
	s_mul_hi_u32 s71, s49, s72
	s_mul_i32 s72, s71, s56
	s_sub_i32 s49, s49, s72
	s_add_i32 s73, s71, 1
	s_sub_i32 s72, s49, s56
	s_cmp_ge_u32 s49, s56
	s_cselect_b32 s71, s73, s71
	s_cselect_b32 s49, s72, s49
	s_add_i32 s72, s71, 1
	s_cmp_ge_u32 s49, s56
	s_cselect_b32 s49, s72, s71
	s_xor_b32 s49, s49, s70
	s_sub_i32 s70, s49, s70
	s_mul_i32 s49, s70, s51
	s_sub_i32 s47, s47, s49
	s_add_i32 s72, s50, s47
	s_mov_b32 s100, 0x82465310
	s_mov_b32 s101, 0x7
	s_lshr_b32 s99, s70, 1
	s_lshl_b32 s99, s99, 2
	s_lshr_b64 s[100:101], s[100:101], s99
	s_and_b32 s100, s100, 15
	s_and_b32 s99, s70, 1
	s_lshl_b32 s100, s100, 1
	s_or_b32 s70, s100, s99
	s_mov_b32 s56, s30

.LBB0_333:
	v_readlane_b32 s9, v241, 22
	s_mov_b32 s46, s9
	s_mov_b32 s100, 0x82465310
	s_mov_b32 s101, 0x7
	s_lshr_b32 s99, s46, 1
	s_lshl_b32 s99, s99, 2
	s_lshr_b64 s[100:101], s[100:101], s99
	s_and_b32 s100, s100, 15
	s_and_b32 s99, s46, 1
	s_lshl_b32 s100, s100, 1
	s_or_b32 s46, s100, s99
	v_readlane_b32 s9, v241, 21
	v_readlane_b32 s57, v242, 10
	s_mov_b32 s48, s9
	s_andn2_b64 vcc, exec, s[26:27]
	s_cbranch_vccz .LBB0_115

	.amdhsa_kernel _Z10hybrid_fwd4Args
		.amdhsa_group_segment_fixed_size 0
		.amdhsa_private_segment_fixed_size 0
		.amdhsa_kernarg_size 440
		.amdhsa_user_sgpr_count 2
		.amdhsa_user_sgpr_dispatch_ptr 0
		.amdhsa_user_sgpr_queue_ptr 0
		.amdhsa_user_sgpr_kernarg_segment_ptr 1
		.amdhsa_user_sgpr_dispatch_id 0
		.amdhsa_user_sgpr_kernarg_preload_length 0
		.amdhsa_user_sgpr_kernarg_preload_offset 0
		.amdhsa_user_sgpr_private_segment_size 0
		.amdhsa_uses_dynamic_stack 0
		.amdhsa_enable_private_segment 0
		.amdhsa_system_sgpr_workgroup_id_x 1
		.amdhsa_system_sgpr_workgroup_id_y 0
		.amdhsa_system_sgpr_workgroup_id_z 0
		.amdhsa_system_sgpr_workgroup_info 0
		.amdhsa_system_vgpr_workitem_id 2
		.amdhsa_next_free_vgpr 243
		.amdhsa_next_free_sgpr 102
		.amdhsa_accum_offset 244
		.amdhsa_reserve_vcc 1
		.amdhsa_float_round_mode_32 0
		.amdhsa_float_round_mode_16_64 0
		.amdhsa_float_denorm_mode_32 3
		.amdhsa_float_denorm_mode_16_64 3
		.amdhsa_dx10_clamp 1
		.amdhsa_ieee_mode 1
		.amdhsa_fp16_overflow 0
		.amdhsa_tg_split 0
		.amdhsa_exception_fp_ieee_invalid_op 0
		.amdhsa_exception_fp_denorm_src 0
		.amdhsa_exception_fp_ieee_div_zero 0
		.amdhsa_exception_fp_ieee_overflow 0
		.amdhsa_exception_fp_ieee_underflow 0
		.amdhsa_exception_fp_ieee_inexact 0
		.amdhsa_exception_int_div_zero 0
	.end_amdhsa_kernel

amdhsa.kernels:
  - .agpr_count:     0
    .args:
      - .offset:         0
        .size:           184
        .value_kind:     by_value
      - .offset:         184
        .size:           4
        .value_kind:     hidden_block_count_x
      - .offset:         188
        .size:           4
        .value_kind:     hidden_block_count_y
      - .offset:         192
        .size:           4
        .value_kind:     hidden_block_count_z
      - .offset:         196
        .size:           2
        .value_kind:     hidden_group_size_x
      - .offset:         198
        .size:           2
        .value_kind:     hidden_group_size_y
      - .offset:         200
        .size:           2
        .value_kind:     hidden_group_size_z
      - .offset:         202
        .size:           2
        .value_kind:     hidden_remainder_x
      - .offset:         204
        .size:           2
        .value_kind:     hidden_remainder_y
      - .offset:         206
        .size:           2
        .value_kind:     hidden_remainder_z
      - .offset:         224
        .size:           8
        .value_kind:     hidden_global_offset_x
      - .offset:         232
        .size:           8
        .value_kind:     hidden_global_offset_y
      - .offset:         240
        .size:           8
        .value_kind:     hidden_global_offset_z
      - .offset:         248
        .size:           2
        .value_kind:     hidden_grid_dims
      - .offset:         272
        .size:           8
        .value_kind:     hidden_multigrid_sync_arg
      - .offset:         304
        .size:           4
        .value_kind:     hidden_dynamic_lds_size
    .group_segment_fixed_size: 0
    .kernarg_segment_align: 8
    .kernarg_segment_size: 440
    .language:       OpenCL C
    .language_version:
      - 2
      - 0
    .max_flat_workgroup_size: 512
    .name:           _Z10hybrid_fwd4Args
    .private_segment_fixed_size: 0
    .sgpr_count:     108
    .sgpr_spill_count: 139
    .symbol:         _Z10hybrid_fwd4Args.kd
    .uniform_work_group_size: 1
    .uses_dynamic_stack: false
    .vgpr_count:     243
    .vgpr_spill_count: 0
    .wavefront_size: 64
